# also rewrote the MLA dense attention tile loop (L2, DK96): per-lane pointer+stride loader, hoisted LDS reads, exp/PV interleave
# speedup vs baseline: 1.0105x; 1.0105x over previous
.Lam96_pre:
	s_movk_i32 s50, 0xff80
	s_mov_b32 s51, -1
	s_lshl_b32 s11, s82, 7
	v_add_u32_e32 v138, s3, v135
	v_ashrrev_i32_e32 v139, 31, v138
	s_and_saveexec_b64 s[26:27], vcc
	v_mad_i64_i32 v[140:141], s[42:43], v138, s82, 0
	v_mov_b32_e32 v142, s86
	v_mov_b32_e32 v143, s87
	v_lshl_add_u64 v[140:141], v[140:141], 1, v[142:143]
	v_lshl_add_u64 v[140:141], v[140:141], 0, s[0:1]
	v_lshl_add_u64 v[240:241], v[108:109], 1, v[140:141]
	v_mov_b32_e32 v246, s11
	s_andn2_b64 exec, s[26:27], vcc
	v_lshlrev_b64 v[140:141], 6, v[138:139]
	v_lshl_add_u64 v[140:141], s[88:89], 0, v[140:141]
	v_lshl_add_u64 v[140:141], v[110:111], 1, v[140:141]
	v_lshl_add_u64 v[240:241], v[140:141], 0, s[50:51]
	v_mov_b32_e32 v246, 0x1000
	s_mov_b64 exec, s[26:27]
	v_mov_b32_e32 v247, 0
	s_and_b64 s[48:49], exec, s[38:39]
	s_cbranch_scc0 .Lam96_sk2_c
	v_add_u32_e32 v138, s3, v133
	v_ashrrev_i32_e32 v139, 31, v138
	s_and_saveexec_b64 s[26:27], s[40:41]
	v_mad_i64_i32 v[140:141], s[42:43], v138, s82, 0
	v_mov_b32_e32 v142, s86
	v_mov_b32_e32 v143, s87
	v_lshl_add_u64 v[140:141], v[140:141], 1, v[142:143]
	v_lshl_add_u64 v[140:141], v[140:141], 0, s[0:1]
	v_lshl_add_u64 v[242:243], v[112:113], 1, v[140:141]
	v_mov_b32_e32 v208, s11
	s_andn2_b64 exec, s[26:27], s[40:41]
	v_lshlrev_b64 v[140:141], 6, v[138:139]
	v_lshl_add_u64 v[140:141], s[88:89], 0, v[140:141]
	v_lshl_add_u64 v[140:141], v[114:115], 1, v[140:141]
	v_lshl_add_u64 v[242:243], v[140:141], 0, s[50:51]
	v_mov_b32_e32 v208, 0x1000
	s_mov_b64 exec, s[26:27]
	v_mov_b32_e32 v209, 0
.Lam96_sk2_c:
	v_add_u32_e32 v138, s3, v134
	v_mad_i64_i32 v[140:141], s[42:43], v138, s82, 0
	v_mov_b32_e32 v142, s90
	v_mov_b32_e32 v143, s91
	v_lshl_add_u64 v[140:141], v[140:141], 1, v[142:143]
	v_lshl_add_u64 v[140:141], v[140:141], 0, s[0:1]
	v_lshl_add_u64 v[244:245], v[140:141], 0, v[0:1]
	v_mov_b32_e32 v136, s11
	v_mov_b32_e32 v137, 0
	v_sub_f32_e32 v216, 0, v132
	v_sub_f32_e32 v217, 0, v132
	v_sub_f32_e32 v218, 0, v132
	v_sub_f32_e32 v219, 0, v132
	v_sub_f32_e32 v220, 0, v132
	v_sub_f32_e32 v221, 0, v132
	v_sub_f32_e32 v222, 0, v132
	v_sub_f32_e32 v223, 0, v132
	v_sub_f32_e32 v224, 0, v132
	v_sub_f32_e32 v225, 0, v132
	v_sub_f32_e32 v226, 0, v132
	v_sub_f32_e32 v227, 0, v132
	v_sub_f32_e32 v228, 0, v132
	v_sub_f32_e32 v229, 0, v132
	v_sub_f32_e32 v230, 0, v132
	v_sub_f32_e32 v231, 0, v132
.Lam96_top:
	s_add_i32 s10, s25, -1
	s_bitcmp1_b32 s10, 0
	s_cselect_b32 s2, 0x5000, 0
	v_add_u32_e32 v138, s2, v125
	v_add_u32_e32 v139, s2, v126
	ds_read_b128 v[148:151], v138
	ds_read_b128 v[152:155], v139
	ds_read_b128 v[156:159], v138 offset:64
	ds_read_b128 v[160:163], v139 offset:64
	ds_read_b128 v[164:167], v138 offset:128
	ds_read_b128 v[168:171], v139 offset:128
	ds_read_b128 v[172:175], v138 offset:6144
	ds_read_b128 v[176:179], v139 offset:6144
	ds_read_b128 v[180:183], v138 offset:6208
	ds_read_b128 v[184:187], v139 offset:6208
	ds_read_b128 v[188:191], v138 offset:6272
	ds_read_b128 v[192:195], v139 offset:6272
	s_cmp_lg_u32 s10, 7
	s_cbranch_scc1 .Lam96_ptr_ok
	s_movk_i32 s50, 0xff80
	s_mov_b32 s51, -1
	s_lshl_b32 s11, s84, 7
	v_add_u32_e32 v138, s24, v135
	v_add_u32_e32 v138, 0x180, v138
	v_ashrrev_i32_e32 v139, 31, v138
	s_and_saveexec_b64 s[26:27], vcc
	v_mad_i64_i32 v[140:141], s[42:43], v138, s84, 0
	v_mov_b32_e32 v142, s70
	v_mov_b32_e32 v143, s71
	v_lshl_add_u64 v[140:141], v[140:141], 1, v[142:143]
	v_lshl_add_u64 v[140:141], v[140:141], 0, s[0:1]
	v_lshl_add_u64 v[240:241], v[108:109], 1, v[140:141]
	v_mov_b32_e32 v246, s11
	s_andn2_b64 exec, s[26:27], vcc
	v_lshlrev_b64 v[140:141], 6, v[138:139]
	v_lshl_add_u64 v[140:141], s[20:21], 0, v[140:141]
	v_lshl_add_u64 v[140:141], v[110:111], 1, v[140:141]
	v_lshl_add_u64 v[240:241], v[140:141], 0, s[50:51]
	v_mov_b32_e32 v246, 0x1000
	s_mov_b64 exec, s[26:27]
	v_mov_b32_e32 v247, 0
	s_and_b64 s[48:49], exec, s[38:39]
	s_cbranch_scc0 .Lam96_sk2_l
	v_add_u32_e32 v138, s24, v133
	v_add_u32_e32 v138, 0x180, v138
	v_ashrrev_i32_e32 v139, 31, v138
	s_and_saveexec_b64 s[26:27], s[40:41]
	v_mad_i64_i32 v[140:141], s[42:43], v138, s84, 0
	v_mov_b32_e32 v142, s70
	v_mov_b32_e32 v143, s71
	v_lshl_add_u64 v[140:141], v[140:141], 1, v[142:143]
	v_lshl_add_u64 v[140:141], v[140:141], 0, s[0:1]
	v_lshl_add_u64 v[242:243], v[112:113], 1, v[140:141]
	v_mov_b32_e32 v208, s11
	s_andn2_b64 exec, s[26:27], s[40:41]
	v_lshlrev_b64 v[140:141], 6, v[138:139]
	v_lshl_add_u64 v[140:141], s[20:21], 0, v[140:141]
	v_lshl_add_u64 v[140:141], v[114:115], 1, v[140:141]
	v_lshl_add_u64 v[242:243], v[140:141], 0, s[50:51]
	v_mov_b32_e32 v208, 0x1000
	s_mov_b64 exec, s[26:27]
	v_mov_b32_e32 v209, 0
.Lam96_sk2_l:
	v_add_u32_e32 v138, s24, v134
	v_add_u32_e32 v138, 0x180, v138
	v_mad_i64_i32 v[140:141], s[42:43], v138, s84, 0
	v_mov_b32_e32 v142, s6
	v_mov_b32_e32 v143, s7
	v_lshl_add_u64 v[140:141], v[140:141], 1, v[142:143]
	v_lshl_add_u64 v[140:141], v[140:141], 0, s[0:1]
	v_lshl_add_u64 v[244:245], v[140:141], 0, v[0:1]
	v_mov_b32_e32 v136, s11
	v_mov_b32_e32 v137, 0
.Lam96_ptr_ok:
	global_load_dwordx4 v[94:97], v[240:241], off
	s_and_b64 s[48:49], exec, s[38:39]
	s_cbranch_scc0 .Lam96_nol2
	global_load_dwordx4 v[90:93], v[242:243], off
	v_lshl_add_u64 v[242:243], v[242:243], 0, v[208:209]
.Lam96_nol2:
	global_load_dwordx4 v[98:101], v[244:245], off
	v_lshl_add_u64 v[240:241], v[240:241], 0, v[246:247]
	v_lshl_add_u64 v[244:245], v[244:245], 0, v[136:137]
	s_waitcnt lgkmcnt(11)
	v_mfma_f32_32x32x16_bf16 v[50:65], v[148:151], v[86:89], v[216:231]
	s_waitcnt lgkmcnt(10)
	v_mfma_f32_32x32x16_bf16 v[50:65], v[152:155], v[82:85], v[50:65]
	s_waitcnt lgkmcnt(9)
	v_mfma_f32_32x32x16_bf16 v[50:65], v[156:159], v[78:81], v[50:65]
	s_waitcnt lgkmcnt(8)
	v_mfma_f32_32x32x16_bf16 v[50:65], v[160:163], v[74:77], v[50:65]
	s_waitcnt lgkmcnt(7)
	v_mfma_f32_32x32x16_bf16 v[50:65], v[164:167], v[70:73], v[50:65]
	s_waitcnt lgkmcnt(6)
	v_mfma_f32_32x32x16_bf16 v[50:65], v[168:171], v[66:69], v[50:65]
	s_waitcnt lgkmcnt(5)
	v_mfma_f32_32x32x16_bf16 v[34:49], v[172:175], v[86:89], v[216:231]
	s_waitcnt lgkmcnt(4)
	v_mfma_f32_32x32x16_bf16 v[34:49], v[176:179], v[82:85], v[34:49]
	s_waitcnt lgkmcnt(3)
	v_mfma_f32_32x32x16_bf16 v[34:49], v[180:183], v[78:81], v[34:49]
	s_waitcnt lgkmcnt(2)
	v_mfma_f32_32x32x16_bf16 v[34:49], v[184:187], v[74:77], v[34:49]
	s_waitcnt lgkmcnt(1)
	v_mfma_f32_32x32x16_bf16 v[34:49], v[188:191], v[70:73], v[34:49]
	s_waitcnt lgkmcnt(0)
	v_mfma_f32_32x32x16_bf16 v[34:49], v[192:195], v[66:69], v[34:49]
	v_add3_u32 v144, s2, v127, v128
	v_add_u32_e32 v145, s2, v129
	ds_read_b64_tr_b16 v[148:149], v144 offset:12288
	ds_read_b64_tr_b16 v[150:151], v144 offset:13312
	ds_read_b64_tr_b16 v[152:153], v145 offset:12288
	ds_read_b64_tr_b16 v[154:155], v145 offset:13312
	ds_read_b64_tr_b16 v[156:157], v144 offset:14336
	ds_read_b64_tr_b16 v[158:159], v144 offset:15360
	ds_read_b64_tr_b16 v[160:161], v145 offset:14336
	ds_read_b64_tr_b16 v[162:163], v145 offset:15360
	ds_read_b64_tr_b16 v[164:165], v144 offset:16384
	ds_read_b64_tr_b16 v[166:167], v144 offset:17408
	ds_read_b64_tr_b16 v[168:169], v145 offset:16384
	ds_read_b64_tr_b16 v[170:171], v145 offset:17408
	v_max3_f32 v142, v50, v51, v52
	v_max3_f32 v142, v142, v53, v54
	v_max3_f32 v142, v142, v55, v56
	v_max3_f32 v142, v142, v57, v58
	v_max3_f32 v142, v142, v59, v60
	v_max3_f32 v142, v142, v61, v62
	v_max3_f32 v142, v142, v63, v64
	v_max3_f32 v143, v34, v35, v36
	v_max3_f32 v143, v143, v37, v38
	v_max3_f32 v143, v143, v39, v40
	v_max3_f32 v143, v143, v41, v42
	v_max3_f32 v143, v143, v43, v44
	v_max3_f32 v143, v143, v45, v46
	v_max3_f32 v143, v143, v47, v48
	v_max3_f32 v142, v142, v143, v65
	v_max_f32_e32 v142, v142, v49
	v_mov_b32_e32 v143, v142
	s_nop 1
	v_permlane32_swap_b32_e32 v142, v143
	v_max_f32_e32 v142, v142, v143
	s_mov_b32 s11, 0x41000000
	v_cmp_ge_f32_e64 s[42:43], s11, v142
	s_cmp_eq_u64 s[42:43], exec
	s_cbranch_scc0 .Lam96_resc
.Lam96_exp:
	v_exp_f32_e32 v50, v50
	v_exp_f32_e32 v51, v51
	v_exp_f32_e32 v52, v52
	v_exp_f32_e32 v53, v53
	v_exp_f32_e32 v54, v54
	v_exp_f32_e32 v55, v55
	v_exp_f32_e32 v56, v56
	v_exp_f32_e32 v57, v57
	v_cvt_pk_bf16_f32 v196, v50, v51
	v_cvt_pk_bf16_f32 v197, v52, v53
	v_cvt_pk_bf16_f32 v198, v54, v55
	v_cvt_pk_bf16_f32 v199, v56, v57
	v_add_f32_e32 v142, v50, v51
	v_add_f32_e32 v143, v52, v53
	v_add_f32_e32 v142, v142, v54
	v_add_f32_e32 v143, v143, v55
	v_add_f32_e32 v142, v142, v56
	v_add_f32_e32 v143, v143, v57
	v_add_f32_e32 v131, v131, v142
	v_add_f32_e32 v131, v131, v143
	s_waitcnt lgkmcnt(10)
	v_mfma_f32_32x32x16_bf16 v[18:33], v[148:151], v[196:199], v[18:33]
	s_waitcnt lgkmcnt(8)
	v_mfma_f32_32x32x16_bf16 v[2:17], v[152:155], v[196:199], v[2:17]
	ds_read_b64_tr_b16 v[172:173], v144 offset:18432
	ds_read_b64_tr_b16 v[174:175], v144 offset:19456
	ds_read_b64_tr_b16 v[176:177], v145 offset:18432
	ds_read_b64_tr_b16 v[178:179], v145 offset:19456
	v_exp_f32_e32 v58, v58
	v_exp_f32_e32 v59, v59
	v_exp_f32_e32 v60, v60
	v_exp_f32_e32 v61, v61
	v_exp_f32_e32 v62, v62
	v_exp_f32_e32 v63, v63
	v_exp_f32_e32 v64, v64
	v_exp_f32_e32 v65, v65
	v_cvt_pk_bf16_f32 v200, v58, v59
	v_cvt_pk_bf16_f32 v201, v60, v61
	v_cvt_pk_bf16_f32 v202, v62, v63
	v_cvt_pk_bf16_f32 v203, v64, v65
	v_add_f32_e32 v142, v58, v59
	v_add_f32_e32 v143, v60, v61
	v_add_f32_e32 v142, v142, v62
	v_add_f32_e32 v143, v143, v63
	v_add_f32_e32 v142, v142, v64
	v_add_f32_e32 v143, v143, v65
	v_add_f32_e32 v131, v131, v142
	v_add_f32_e32 v131, v131, v143
	s_waitcnt lgkmcnt(10)
	v_mfma_f32_32x32x16_bf16 v[18:33], v[156:159], v[200:203], v[18:33]
	s_waitcnt lgkmcnt(8)
	v_mfma_f32_32x32x16_bf16 v[2:17], v[160:163], v[200:203], v[2:17]
	v_exp_f32_e32 v34, v34
	v_exp_f32_e32 v35, v35
	v_exp_f32_e32 v36, v36
	v_exp_f32_e32 v37, v37
	v_exp_f32_e32 v38, v38
	v_exp_f32_e32 v39, v39
	v_exp_f32_e32 v40, v40
	v_exp_f32_e32 v41, v41
	v_cvt_pk_bf16_f32 v204, v34, v35
	v_cvt_pk_bf16_f32 v205, v36, v37
	v_cvt_pk_bf16_f32 v206, v38, v39
	v_cvt_pk_bf16_f32 v207, v40, v41
	v_add_f32_e32 v142, v34, v35
	v_add_f32_e32 v143, v36, v37
	v_add_f32_e32 v142, v142, v38
	v_add_f32_e32 v143, v143, v39
	v_add_f32_e32 v142, v142, v40
	v_add_f32_e32 v143, v143, v41
	v_add_f32_e32 v131, v131, v142
	v_add_f32_e32 v131, v131, v143
	s_waitcnt lgkmcnt(6)
	v_mfma_f32_32x32x16_bf16 v[18:33], v[164:167], v[204:207], v[18:33]
	s_waitcnt lgkmcnt(4)
	v_mfma_f32_32x32x16_bf16 v[2:17], v[168:171], v[204:207], v[2:17]
	v_exp_f32_e32 v42, v42
	v_exp_f32_e32 v43, v43
	v_exp_f32_e32 v44, v44
	v_exp_f32_e32 v45, v45
	v_exp_f32_e32 v46, v46
	v_exp_f32_e32 v47, v47
	v_exp_f32_e32 v48, v48
	v_exp_f32_e32 v49, v49
	v_cvt_pk_bf16_f32 v232, v42, v43
	v_cvt_pk_bf16_f32 v233, v44, v45
	v_cvt_pk_bf16_f32 v234, v46, v47
	v_cvt_pk_bf16_f32 v235, v48, v49
	v_add_f32_e32 v142, v42, v43
	v_add_f32_e32 v143, v44, v45
	v_add_f32_e32 v142, v142, v46
	v_add_f32_e32 v143, v143, v47
	v_add_f32_e32 v142, v142, v48
	v_add_f32_e32 v143, v143, v49
	v_add_f32_e32 v131, v131, v142
	v_add_f32_e32 v131, v131, v143
	s_waitcnt lgkmcnt(2)
	v_mfma_f32_32x32x16_bf16 v[18:33], v[172:175], v[232:235], v[18:33]
	s_waitcnt lgkmcnt(0)
	v_mfma_f32_32x32x16_bf16 v[2:17], v[176:179], v[232:235], v[2:17]
	s_bitcmp1_b32 s25, 0
	s_cselect_b32 s26, 0x5000, 0
	v_add3_u32 v138, s26, v119, v118
	v_add3_u32 v139, s26, v121, v120
	v_add3_u32 v140, s26, v122, v123
	s_waitcnt vmcnt(1)
	ds_write_b128 v138, v[94:97]
	s_and_b64 s[48:49], exec, s[38:39]
	s_cbranch_scc0 .Lam96_nos2
	ds_write_b128 v139, v[90:93]
.Lam96_nos2:
	s_waitcnt vmcnt(0)
	ds_write_b128 v140, v[98:101] offset:12288
	s_add_i32 s25, s25, 1
	s_waitcnt lgkmcnt(0)
	s_barrier
	s_cmp_lg_u32 s25, 40
	s_cbranch_scc1 .Lam96_top
	s_mov_b32 s2, 0x41000000
	s_branch .LBB0_333
.Lam96_resc:
	v_max_f32_e32 v143, 0, v142
	v_add_f32_e32 v132, v132, v143
	v_exp_f32_e64 v142, -v143
	v_sub_f32_e32 v216, 0, v132
	v_sub_f32_e32 v217, 0, v132
	v_sub_f32_e32 v218, 0, v132
	v_sub_f32_e32 v219, 0, v132
	v_sub_f32_e32 v220, 0, v132
	v_sub_f32_e32 v221, 0, v132
	v_sub_f32_e32 v222, 0, v132
	v_sub_f32_e32 v223, 0, v132
	v_sub_f32_e32 v224, 0, v132
	v_sub_f32_e32 v225, 0, v132
	v_sub_f32_e32 v226, 0, v132
	v_sub_f32_e32 v227, 0, v132
	v_sub_f32_e32 v228, 0, v132
	v_sub_f32_e32 v229, 0, v132
	v_sub_f32_e32 v230, 0, v132
	v_sub_f32_e32 v231, 0, v132
	v_sub_f32_e32 v34, v34, v143
	v_sub_f32_e32 v35, v35, v143
	v_sub_f32_e32 v36, v36, v143
	v_sub_f32_e32 v37, v37, v143
	v_sub_f32_e32 v38, v38, v143
	v_sub_f32_e32 v39, v39, v143
	v_sub_f32_e32 v40, v40, v143
	v_sub_f32_e32 v41, v41, v143
	v_sub_f32_e32 v42, v42, v143
	v_sub_f32_e32 v43, v43, v143
	v_sub_f32_e32 v44, v44, v143
	v_sub_f32_e32 v45, v45, v143
	v_sub_f32_e32 v46, v46, v143
	v_sub_f32_e32 v47, v47, v143
	v_sub_f32_e32 v48, v48, v143
	v_sub_f32_e32 v49, v49, v143
	v_sub_f32_e32 v50, v50, v143
	v_sub_f32_e32 v51, v51, v143
	v_sub_f32_e32 v52, v52, v143
	v_sub_f32_e32 v53, v53, v143
	v_sub_f32_e32 v54, v54, v143
	v_sub_f32_e32 v55, v55, v143
	v_sub_f32_e32 v56, v56, v143
	v_sub_f32_e32 v57, v57, v143
	v_sub_f32_e32 v58, v58, v143
	v_sub_f32_e32 v59, v59, v143
	v_sub_f32_e32 v60, v60, v143
	v_sub_f32_e32 v61, v61, v143
	v_sub_f32_e32 v62, v62, v143
	v_sub_f32_e32 v63, v63, v143
	v_sub_f32_e32 v64, v64, v143
	v_sub_f32_e32 v65, v65, v143
	v_mul_f32_e32 v2, v2, v142
	v_mul_f32_e32 v3, v3, v142
	v_mul_f32_e32 v4, v4, v142
	v_mul_f32_e32 v5, v5, v142
	v_mul_f32_e32 v6, v6, v142
	v_mul_f32_e32 v7, v7, v142
	v_mul_f32_e32 v8, v8, v142
	v_mul_f32_e32 v9, v9, v142
	v_mul_f32_e32 v10, v10, v142
	v_mul_f32_e32 v11, v11, v142
	v_mul_f32_e32 v12, v12, v142
	v_mul_f32_e32 v13, v13, v142
	v_mul_f32_e32 v14, v14, v142
	v_mul_f32_e32 v15, v15, v142
	v_mul_f32_e32 v16, v16, v142
	v_mul_f32_e32 v17, v17, v142
	v_mul_f32_e32 v18, v18, v142
	v_mul_f32_e32 v19, v19, v142
	v_mul_f32_e32 v20, v20, v142
	v_mul_f32_e32 v21, v21, v142
	v_mul_f32_e32 v22, v22, v142
	v_mul_f32_e32 v23, v23, v142
	v_mul_f32_e32 v24, v24, v142
	v_mul_f32_e32 v25, v25, v142
	v_mul_f32_e32 v26, v26, v142
	v_mul_f32_e32 v27, v27, v142
	v_mul_f32_e32 v28, v28, v142
	v_mul_f32_e32 v29, v29, v142
	v_mul_f32_e32 v30, v30, v142
	v_mul_f32_e32 v31, v31, v142
	v_mul_f32_e32 v32, v32, v142
	v_mul_f32_e32 v33, v33, v142
	v_mul_f32_e32 v131, v131, v142
	s_branch .Lam96_exp
